# mixprep workgroup-to-row-block mapping made XCD-contiguous (window rows shared through the XCD L2), on v044
# speedup vs baseline: 1.0039x; 1.0005x over previous
; DI int opaque_tid() { int t; asm volatile("v_mov_b32 %0, %1" : "=v"(t) : "v"((int)threadIdx.x)); return t; }
; DI void mixprep_phase(const bf16_t* Hm, const float* convw, bf16_t* DP, bf16_t* CAT, int gtid, int nthr) {
;     const int NG = M * 32, NIT = M * 128;
;     for (int it = gtid; it < NG; it += nthr) { const int m = it >> 5, c = it & 31;
; __global__ void __launch_bounds__(NTHREADS, 2) mega_fwd(Args a) {
;     ...
;             if (ph == 4 && cv >= 32) {
;                 const int tid = opaque_tid();
;                 mixprep_phase(BIG, a.in[9], CAT, CAT, (cv - 32) * NTHREADS + tid, (G - 32) * NTHREADS);
.LBB0_134:
	s_andn2_b64 vcc, exec, s[0:1]
	s_cbranch_vccnz .LBB0_146
	s_and_b32 s0, s2, 7
	s_mul_i32 s0, s0, 28
	s_lshr_b32 s6, s2, 3
	s_add_i32 s0, s0, s6
	s_sub_i32 s0, s0, 4
	s_lshl_b32 s0, s0, 9
	s_waitcnt vmcnt(0)
	v_mov_b32 v0, v188
	s_mov_b32 s6, s43
	v_add_u32_e32 v20, s0, v0
	s_mov_b32 s0, 0x40000
	v_cmp_gt_i32_e32 vcc, s0, v20
	v_lshlrev_b32_e32 v21, 3, v20
	s_and_saveexec_b64 s[74:75], vcc
	v_readlane_b32 s26, v255, 6
	v_readlane_b32 s36, v255, 8
	v_readlane_b32 s27, v255, 7
	v_readlane_b32 s37, v255, 9
	v_readlane_b32 s46, v253, 29
	v_readlane_b32 s47, v254, 53
	s_cbranch_execz .LBB0_138
	v_lshlrev_b32_e32 v1, 3, v20
	s_mov_b64 s[76:77], 0
	v_mov_b32_e32 v5, v20
